# v55 + kernel-start silu(c) staging de-serialised (6 loads in flight, one wait; same silu instruction sequence)
# speedup vs baseline: 1.0008x; 1.0008x over previous
; __global__ void __launch_bounds__(NTHREADS, 2) mega_fwd(Params P) {
;     ...
;         for (int i = tid; i < 3 * DM; i += NTHREADS) { const int v = i / DM, k = i % DM; const float cv = (v < 2) ? P.c[v * DM + k] : P.c_ctx[k]; scv[i] = cv / (1.0f + __expf(-cv)); }
.LBB0_4:
	s_or_b64 exec, exec, s[4:5]
	s_load_dwordx16 s[4:19], s[0:1], 0x0
	v_mov_b32 v1, v214
	s_waitcnt lgkmcnt(0)
	v_writelane_b32 v253, s4, 9
	s_nop 1
	v_writelane_b32 v253, s5, 10
	v_writelane_b32 v253, s6, 11
	v_writelane_b32 v253, s7, 12
	v_writelane_b32 v253, s8, 13
	v_writelane_b32 v253, s9, 14
	v_writelane_b32 v253, s10, 15
	v_writelane_b32 v253, s11, 16
	v_writelane_b32 v253, s12, 17
	v_writelane_b32 v253, s13, 18
	v_writelane_b32 v253, s14, 19
	v_writelane_b32 v253, s15, 20
	v_writelane_b32 v253, s16, 21
	v_writelane_b32 v253, s17, 22
	v_writelane_b32 v253, s18, 23
	v_writelane_b32 v253, s19, 24
	s_movk_i32 s4, 0xc00
	v_readfirstlane_b32 s20, v1
	v_cmp_gt_i32_e32 vcc, s4, v1
	s_and_saveexec_b64 s[4:5], vcc
	s_cbranch_execz .LBB0_11
	s_load_dwordx16 s[40:55], s[0:1], 0x0
	v_lshlrev_b32_e32 v2, 2, v1
	v_mov_b32_e32 v3, 0
	v_add_u32_e32 v6, 0x11000, v2
	s_mov_b64 s[8:9], 0x1000
	s_waitcnt lgkmcnt(0)
	v_lshl_add_u64 v[18:19], s[42:43], 0, v[2:3]
	v_lshl_add_u64 v[22:23], s[46:47], 0, v[2:3]
	v_lshl_add_u64 v[20:21], v[18:19], 0, s[8:9]
	global_load_dword v12, v[18:19], off
	global_load_dword v13, v[18:19], off offset:2048
	global_load_dword v14, v[20:21], off
	global_load_dword v15, v[20:21], off offset:2048
	global_load_dword v16, v[22:23], off
	global_load_dword v17, v[22:23], off offset:2048
	s_waitcnt vmcnt(0)
	v_mul_f32_e32 v4, 0xbfb8aa3b, v12
	v_exp_f32_e32 v4, v4
	s_nop 0
	v_add_f32_e32 v4, 1.0, v4
	v_div_scale_f32 v7, s[8:9], v4, v4, v12
	v_rcp_f32_e32 v8, v7
	v_div_scale_f32 v9, vcc, v12, v4, v12
	v_fma_f32 v10, -v7, v8, 1.0
	v_fmac_f32_e32 v8, v10, v8
	v_mul_f32_e32 v10, v9, v8
	v_fma_f32 v11, -v7, v10, v9
	v_fmac_f32_e32 v10, v11, v8
	v_fma_f32 v7, -v7, v10, v9
	v_div_fmas_f32 v7, v7, v8, v10
	v_div_fixup_f32 v12, v7, v4, v12
	ds_write_b32 v6, v12
	v_mul_f32_e32 v4, 0xbfb8aa3b, v13
	v_exp_f32_e32 v4, v4
	s_nop 0
	v_add_f32_e32 v4, 1.0, v4
	v_div_scale_f32 v7, s[8:9], v4, v4, v13
	v_rcp_f32_e32 v8, v7
	v_div_scale_f32 v9, vcc, v13, v4, v13
	v_fma_f32 v10, -v7, v8, 1.0
	v_fmac_f32_e32 v8, v10, v8
	v_mul_f32_e32 v10, v9, v8
	v_fma_f32 v11, -v7, v10, v9
	v_fmac_f32_e32 v10, v11, v8
	v_fma_f32 v7, -v7, v10, v9
	v_div_fmas_f32 v7, v7, v8, v10
	v_div_fixup_f32 v13, v7, v4, v13
	ds_write_b32 v6, v13 offset:2048
	v_mul_f32_e32 v4, 0xbfb8aa3b, v14
	v_exp_f32_e32 v4, v4
	s_nop 0
	v_add_f32_e32 v4, 1.0, v4
	v_div_scale_f32 v7, s[8:9], v4, v4, v14
	v_rcp_f32_e32 v8, v7
	v_div_scale_f32 v9, vcc, v14, v4, v14
	v_fma_f32 v10, -v7, v8, 1.0
	v_fmac_f32_e32 v8, v10, v8
	v_mul_f32_e32 v10, v9, v8
	v_fma_f32 v11, -v7, v10, v9
	v_fmac_f32_e32 v10, v11, v8
	v_fma_f32 v7, -v7, v10, v9
	v_div_fmas_f32 v7, v7, v8, v10
	v_div_fixup_f32 v14, v7, v4, v14
	ds_write_b32 v6, v14 offset:4096
	v_mul_f32_e32 v4, 0xbfb8aa3b, v15
	v_exp_f32_e32 v4, v4
	s_nop 0
	v_add_f32_e32 v4, 1.0, v4
	v_div_scale_f32 v7, s[8:9], v4, v4, v15
	v_rcp_f32_e32 v8, v7
	v_div_scale_f32 v9, vcc, v15, v4, v15
	v_fma_f32 v10, -v7, v8, 1.0
	v_fmac_f32_e32 v8, v10, v8
	v_mul_f32_e32 v10, v9, v8
	v_fma_f32 v11, -v7, v10, v9
	v_fmac_f32_e32 v10, v11, v8
	v_fma_f32 v7, -v7, v10, v9
	v_div_fmas_f32 v7, v7, v8, v10
	v_div_fixup_f32 v15, v7, v4, v15
	ds_write_b32 v6, v15 offset:6144
	v_mul_f32_e32 v4, 0xbfb8aa3b, v16
	v_exp_f32_e32 v4, v4
	s_nop 0
	v_add_f32_e32 v4, 1.0, v4
	v_div_scale_f32 v7, s[8:9], v4, v4, v16
	v_rcp_f32_e32 v8, v7
	v_div_scale_f32 v9, vcc, v16, v4, v16
	v_fma_f32 v10, -v7, v8, 1.0
	v_fmac_f32_e32 v8, v10, v8
	v_mul_f32_e32 v10, v9, v8
	v_fma_f32 v11, -v7, v10, v9
	v_fmac_f32_e32 v10, v11, v8
	v_fma_f32 v7, -v7, v10, v9
	v_div_fmas_f32 v7, v7, v8, v10
	v_div_fixup_f32 v16, v7, v4, v16
	ds_write_b32 v6, v16 offset:8192
	v_mul_f32_e32 v4, 0xbfb8aa3b, v17
	v_exp_f32_e32 v4, v4
	s_nop 0
	v_add_f32_e32 v4, 1.0, v4
	v_div_scale_f32 v7, s[8:9], v4, v4, v17
	v_rcp_f32_e32 v8, v7
	v_div_scale_f32 v9, vcc, v17, v4, v17
	v_fma_f32 v10, -v7, v8, 1.0
	v_fmac_f32_e32 v8, v10, v8
	v_mul_f32_e32 v10, v9, v8
	v_fma_f32 v11, -v7, v10, v9
	v_fmac_f32_e32 v10, v11, v8
	v_fma_f32 v7, -v7, v10, v9
	v_div_fmas_f32 v7, v7, v8, v10
	v_div_fixup_f32 v17, v7, v4, v17
	ds_write_b32 v6, v17 offset:10240
